# phase +3: mlstm_c units after the first taken from a shared ticket counter (workgroups with a short attention range take more units)
# baseline (speedup 1.0000x reference)
.LBB0_1287:
	s_or_b64 exec, exec, s[0:1]
	v_readfirstlane_b32 s100, v211
	s_cmp_lg_u32 s100, 0
	s_cbranch_scc1 .Lmc_nowr
	s_waitcnt vmcnt(0)
	v_readlane_b32 s100, v255, 63
	s_lshr_b32 s100, s100, 6
	s_and_b32 s100, s100, 0x1ff
	s_add_i32 s100, s100, s26
	v_mov_b32_e32 v0, 0x22040
	v_mov_b32_e32 v3, s100
	ds_write_b32 v0, v3
.Lmc_nowr:
	v_lshlrev_b32_e32 v0, 4, v220
	v_bitop3_b32 v0, v0, 64, v221 bitop3:0x36
	v_lshl_add_u32 v0, v0, 2, 0
	s_waitcnt lgkmcnt(0)
	s_barrier
	ds_read_b32 v0, v0 offset:768
	v_mov_b32_e32 v3, 0x22040
	ds_read_b32 v3, v3
	s_lshl_b32 s0, s31, 2
	s_add_u32 s0, s17, s0
	v_lshl_add_u64 v[16:17], v[216:217], 1, s[92:93]
	s_addc_u32 s1, s18, 0
	s_waitcnt lgkmcnt(0)
	v_add_f32_e32 v0, v2, v0
	v_fmamk_f32 v0, v0, 0x3c000000, v210
	v_cmp_gt_f32_e32 vcc, s67, v0
	v_mul_f32_e32 v2, 0x4b800000, v0
	v_lshl_add_u64 v[16:17], v[16:17], 0, s[24:25]
	v_cndmask_b32_e32 v0, v0, v2, vcc
	v_rsq_f32_e32 v0, v0
	v_lshlrev_b64 v[6:7], 12, v[218:219]
	v_readfirstlane_b32 s100, v3
	s_sub_i32 s101, s100, s30
	s_mov_b32 s30, s100
	v_mul_f32_e32 v2, 0x45800000, v0
	v_cndmask_b32_e32 v0, v0, v2, vcc
	v_or_b32_e32 v2, v206, v240
	v_ashrrev_i32_e32 v3, 31, v2
	v_lshlrev_b64 v[18:19], 1, v[2:3]
	v_lshl_add_u64 v[4:5], v[2:3], 2, s[0:1]
	v_lshl_add_u64 v[16:17], v[16:17], 0, v[18:19]
	s_mov_b64 s[0:1], 0x19ca0800
	v_lshl_add_u64 v[2:3], v[16:17], 0, s[0:1]
	v_add_co_u32_e32 v16, vcc, s56, v16
	global_load_dwordx4 v[12:15], v[4:5], off
	s_nop 0
	v_addc_co_u32_e32 v17, vcc, 0, v17, vcc
	global_load_dwordx2 v[16:17], v[16:17], off offset:2048
	v_mul_f32_e32 v22, v58, v0
	v_readlane_b32 s0, v253, 60
	v_readlane_b32 s1, v253, 61
	v_mul_f32_e32 v8, v8, v0
	s_waitcnt vmcnt(1)
	v_mul_f32_e32 v12, v12, v22
	v_lshl_add_u64 v[6:7], s[0:1], 0, v[6:7]
	v_lshl_add_u64 v[6:7], v[6:7], 0, s[24:25]
	s_waitcnt vmcnt(0)
	v_lshlrev_b32_e32 v20, 16, v16
	v_mul_f32_e32 v12, v12, v20
	v_mul_f32_e32 v20, v55, v0
	v_and_b32_e32 v16, 0xffff0000, v16
	v_mul_f32_e32 v13, v13, v20
	v_mul_f32_e32 v13, v13, v16
	v_mul_f32_e32 v16, v56, v0
	v_mul_f32_e32 v14, v14, v16
	v_mul_f32_e32 v16, v57, v0
	v_lshlrev_b32_e32 v21, 16, v17
	v_and_b32_e32 v17, 0xffff0000, v17
	v_mul_f32_e32 v15, v15, v16
	v_lshl_add_u64 v[6:7], v[6:7], 0, v[18:19]
	v_mul_f32_e32 v14, v14, v21
	v_mul_f32_e32 v15, v15, v17
	v_cvt_pk_bf16_f32 v12, v12, v13
	v_cvt_pk_bf16_f32 v13, v14, v15
	global_store_dwordx2 v[6:7], v[12:13], off
	global_load_dwordx4 v[12:15], v[4:5], off offset:64
	s_nop 0
	global_load_dwordx2 v[16:17], v[2:3], off offset:32
	v_mul_f32_e32 v20, v54, v0
	v_readlane_b32 s0, v254, 39
	s_lshl_b32 s19, s30, 4
	v_readlane_b32 s0, v254, 48
	v_readlane_b32 s1, v254, 49
	s_lshl_b32 s0, s101, 2
	s_add_u32 s2, s2, s0
	s_addc_u32 s3, s3, 0
	s_cmpk_gt_i32 s30, 0x1ff
	s_waitcnt vmcnt(1)
	v_mul_f32_e32 v12, v12, v20
	s_waitcnt vmcnt(0)
	v_lshlrev_b32_e32 v18, 16, v16
	v_mul_f32_e32 v12, v12, v18
	v_mul_f32_e32 v18, v50, v0
	v_and_b32_e32 v16, 0xffff0000, v16
	v_mul_f32_e32 v13, v13, v18
	v_mul_f32_e32 v13, v13, v16
	v_mul_f32_e32 v16, v48, v0
	v_mul_f32_e32 v14, v14, v16
	v_mul_f32_e32 v16, v47, v0
	v_lshlrev_b32_e32 v19, 16, v17
	v_and_b32_e32 v17, 0xffff0000, v17
	v_mul_f32_e32 v15, v15, v16
	v_mul_f32_e32 v14, v14, v19
	v_mul_f32_e32 v15, v15, v17
	v_cvt_pk_bf16_f32 v12, v12, v13
	v_cvt_pk_bf16_f32 v13, v14, v15
	global_store_dwordx2 v[6:7], v[12:13], off offset:32
	global_load_dwordx4 v[12:15], v[4:5], off offset:128
	s_nop 0
	global_load_dwordx2 v[16:17], v[2:3], off offset:64
	v_mul_f32_e32 v20, v46, v0
	s_waitcnt vmcnt(1)
	v_mul_f32_e32 v12, v20, v12
	s_waitcnt vmcnt(0)
	v_lshlrev_b32_e32 v18, 16, v16
	v_mul_f32_e32 v12, v12, v18
	v_mul_f32_e32 v18, v42, v0
	v_and_b32_e32 v16, 0xffff0000, v16
	v_mul_f32_e32 v13, v18, v13
	v_mul_f32_e32 v13, v13, v16
	v_mul_f32_e32 v16, v39, v0
	v_mul_f32_e32 v14, v16, v14
	v_mul_f32_e32 v16, v38, v0
	v_lshlrev_b32_e32 v19, 16, v17
	v_and_b32_e32 v17, 0xffff0000, v17
	v_mul_f32_e32 v15, v16, v15
	v_mul_f32_e32 v14, v14, v19
	v_mul_f32_e32 v15, v15, v17
	v_cvt_pk_bf16_f32 v12, v12, v13
	v_cvt_pk_bf16_f32 v13, v14, v15
	global_store_dwordx2 v[6:7], v[12:13], off offset:64
	global_load_dwordx4 v[12:15], v[4:5], off offset:192
	s_nop 0
	global_load_dwordx2 v[2:3], v[2:3], off offset:96
	s_waitcnt vmcnt(1)
	v_mul_f32_e32 v8, v8, v12
	s_waitcnt vmcnt(0)
	v_lshlrev_b32_e32 v4, 16, v2
	v_mul_f32_e32 v4, v8, v4
	v_mul_f32_e32 v8, v9, v0
	v_and_b32_e32 v2, 0xffff0000, v2
	v_mul_f32_e32 v8, v8, v13
	v_mul_f32_e32 v2, v8, v2
	v_mul_f32_e32 v8, v10, v0
	v_mul_f32_e32 v0, v11, v0
	v_lshlrev_b32_e32 v5, 16, v3
	v_and_b32_e32 v3, 0xffff0000, v3
	v_mul_f32_e32 v8, v8, v14
	v_mul_f32_e32 v0, v0, v15
	v_mul_f32_e32 v5, v8, v5
	v_mul_f32_e32 v0, v0, v3
	v_cvt_pk_bf16_f32 v2, v4, v2
	v_cvt_pk_bf16_f32 v3, v5, v0
	global_store_dwordx2 v[6:7], v[2:3], off offset:96
	s_barrier
	s_cbranch_scc1 .LBB0_1362
.LBB0_1288:
	v_readfirstlane_b32 s100, v211
	s_cmp_lg_u32 s100, 0
	s_cbranch_scc1 .Lmc_noat
	s_add_u32 s100, s92, 0x2ad81808
	s_addc_u32 s101, s93, 0
	s_mov_b32 exec_lo, 0
	s_mov_b32 exec_hi, 0x80000000
	global_atomic_add v255, v1, v227, s[100:101] sc0
	s_mov_b64 exec, -1
